# scan chunk 1: recurrence waves touch the attention half of CAT (W_out's A operand, cold by then) so it sits in MALL/L2 when W_out streams it
# baseline (speedup 1.0000x reference)
; #define LAS __attribute__((address_space(3)))
; __device__ __forceinline__ void scan_phase(const Params& P, LAS unsigned char* lds, int tid, int wid, int lane) {
;     ...
;                 const LAS unsigned char* buf = lds + (ck & 1) * SBUF + jq * 16; const LAS unsigned char* vbuf = lds + (ck & 1) * SBUF + 1280 + il * 4; const LAS unsigned char* sbuf = lds + (ck & 1) * SBUF + 1600;
;                 LAS float* yb = (LAS float*)(lds + YOFF + (ck & 1) * 2048);
;                 f32x4 w0[2], kh0[2], kk0[2], b0[2], r0[2], wk0[2], w1[2], kh1[2], b1[2], r1[2]; float v0[2], v1[2]; f32x2v bk[2];
;     ...
;                 SC_LOADP(0, 0);
;                 for (int t0 = 0; t0 < nsteps; t0 += 16) {
.LBB0_879:
	s_andn2_b64 vcc, exec, s[12:13]
	s_cbranch_vccnz .LBB0_858
	s_cmp_lg_u32 s31, 1
	s_cbranch_scc1 .Lmy_pfcat_skip
	v_lshl_add_u32 v226, s33, 8, v209
	v_lshrrev_b32_e32 v227, 2, v226
	v_and_b32_e32 v226, 3, v226
	v_lshlrev_b32_e32 v227, 11, v227
	v_lshl_add_u32 v226, v226, 8, v227
	s_add_u32 s98, s86, 0x2c00000
	s_addc_u32 s99, s87, 0
	global_load_dword v227, v226, s[98:99]
	global_load_dword v227, v226, s[98:99] offset:128
.Lmy_pfcat_skip:
	s_and_b32 s12, s31, 1
	s_mul_i32 s13, s12, 0xca00
	s_add_i32 s36, s13, 0
	v_add_u32_e32 v1, s36, v48
	s_waitcnt vmcnt(3)
	ds_read_b128 v[14:17], v1
	s_waitcnt vmcnt(1)
	ds_read_b128 v[22:25], v1 offset:256
	ds_read_b128 v[42:45], v1 offset:512
	ds_read_b128 v[6:9], v1 offset:1024
	ds_read_b128 v[38:41], v1 offset:1344
	ds_read_b128 v[18:21], v1 offset:1616
	s_waitcnt vmcnt(0)
	ds_read_b128 v[26:29], v1 offset:1872
	ds_read_b128 v[10:13], v1 offset:2640
	v_lshl_add_u32 v63, v134, 2, s36
	v_mov_b32_e32 v65, s36
	ds_read_b128 v[108:111], v63 offset:2960
	v_lshl_add_u32 v65, s12, 11, v135
	s_mov_b32 s37, 0
	s_mov_b64 s[12:13], -1
